# GDN prompt prologue: chunk-1 gate scalars loaded straight into their raw registers, exposed vmcnt waits + moves after the first barrier removed (on top of the HGRN-sample gate batching)
# speedup vs baseline: 1.0027x; 1.0027x over previous
; #define LAS __attribute__((address_space(3)))
;     ...
;         constexpr int BUF = C::OFF_O + 2048;
;         rec_load<MIX, false>(R, proj, 0, sg, head, vcol0);
;         rec_process<MIX, false>(R, par, l, L, 0, sg, head);
;         __syncthreads();
;         rec_load<MIX, false>(R, proj, 1, sg, head, vcol0);
; #pragma unroll 1
;         for (int c = 0; c < SEQ / 64; ++c) {
;             LAS float* Lc = L + (c & 1) * BUF;
; #pragma unroll 1
;             for (int g = 0; g < (act ? 4 : 0); ++g) { float pp[16];
;                 gdn_group8(S, pp, 0, Lc, g * 16, kg, vl); gdn_group8(S, pp, 8, Lc, g * 16 + 8, kg, vl);
;                 Lc[C::OFF_O + (g * 16 + kg) * 32 + vl] = reduce_scatter16(pp, kg); }
;             if (c + 1 < SEQ / 64) { rec_process<MIX, false>(R, par, l, L + ((c + 1) & 1) * BUF, c + 1, sg, head);
;                 if (c + 2 < SEQ / 64) rec_load<MIX, false>(R, proj, c + 2, sg, head, vcol0);
;                 else if (DO_SAMPLE) rec_load<MIX, true>(R, proj, 0, sg, head, vcol0); }
.LBB0_410:
	s_or_b64 exec, exec, s[4:5]
	v_mov_b32_e32 v0, v202
	s_waitcnt lgkmcnt(0)
	s_barrier
	s_lshl_b32 s2, s30, 6
	v_ashrrev_i32_e32 v1, 3, v0
	v_and_b32_e32 v2, 7, v0
	v_add3_u32 v3, v1, s10, 64
	v_mov_b64_e32 v[0:1], s[54:55]
	s_lshl_b32 s11, s34, 5
	v_mad_i64_i32 v[12:13], s[4:5], v3, s18, v[0:1]
	s_lshl_b32 s78, s2, 1
	s_mov_b32 s57, s79
	v_lshl_add_u64 v[8:9], v[12:13], 0, s[78:79]
	v_lshlrev_b32_e32 v0, 4, v2
	v_mov_b32_e32 v1, v17
	s_lshl_b32 s4, s11, 1
	s_mov_b32 s5, s79
	v_lshl_add_u64 v[12:13], v[12:13], 0, s[56:57]
	v_lshlrev_b32_e32 v16, 3, v2
	s_waitcnt vmcnt(0)
	v_lshl_add_u64 v[4:5], v[8:9], 0, v[0:1]
	v_lshl_add_u64 v[8:9], v[8:9], 0, s[4:5]
	v_add_co_u32_e32 v12, vcc, s20, v12
	v_lshl_add_u64 v[8:9], v[8:9], 0, v[16:17]
	s_nop 0
	v_addc_co_u32_e32 v13, vcc, 0, v13, vcc
	v_add_co_u32_e32 v176, vcc, 0x88000, v4
	s_nop 1
	v_addc_co_u32_e32 v177, vcc, 0, v5, vcc
	v_add_co_u32_e32 v178, vcc, 0x88000, v8
	s_nop 1
	v_addc_co_u32_e32 v179, vcc, 0, v9, vcc
	v_add_co_u32_e32 v180, vcc, 0x88000, v12
	s_nop 1
	v_addc_co_u32_e32 v181, vcc, 0, v13, vcc
	global_load_dwordx4 v[0:3], v[4:5], off offset:2048
	s_nop 0
	global_load_dwordx4 v[4:7], v[4:5], off offset:2560
	v_bfe_u32 v21, v10, 4, 2
	global_load_dwordx2 v[8:9], v[8:9], off offset:3072
	v_ashrrev_i32_e32 v11, 4, v10
	global_load_ushort v23, v[12:13], off
	v_and_b32_e32 v20, 15, v10
	global_load_ushort v24, v[12:13], off offset:8
	v_and_b32_e32 v13, 2, v10
	v_and_b32_e32 v22, -4, v11
	s_add_i32 s2, 0, 0x8000
	v_cmp_gt_i32_e64 s[42:43], 32, v22
	s_mov_b32 s12, 0
	v_cmp_gt_u32_e64 s[44:45], 8, v20
	v_cmp_eq_u32_e64 s[48:49], 0, v13
	s_or_b32 s13, s10, 0x80
	v_lshl_add_u32 v26, v20, 4, 0
	v_and_b32_e32 v12, 4, v10
	v_and_b32_e32 v10, 1, v10
	v_cmp_eq_u32_e64 s[50:51], 0, v10
	v_lshlrev_b32_e32 v10, 2, v11
	v_lshlrev_b32_e32 v11, 2, v21
	v_and_or_b32 v10, v10, -16, v11
	v_add_u32_e32 v25, s2, v10
	v_lshlrev_b32_e32 v11, 7, v20
	s_add_i32 s2, 0, 0xc400
	v_add3_u32 v27, v10, v11, s2
	v_mov_b32_e32 v10, 0
	v_cmp_eq_u32_e64 s[46:47], 0, v12
	v_mov_b32_e32 v11, v10
	v_mov_b32_e32 v12, v10
	v_mov_b32_e32 v13, v10
	v_ashrrev_i32_e32 v187, 3, v202
	v_lshlrev_b32_e32 v186, 2, v202
	v_and_b32_e32 v186, 28, v186
	v_lshlrev_b32_e32 v182, 7, v187
	v_lshl_add_u32 v182, v186, 2, v182
	v_add_u32_e32 v184, s10, v187
	v_ashrrev_i32_e32 v185, 31, v184
	v_lshlrev_b64 v[184:185], 11, v[184:185]
	v_lshl_add_u64 v[184:185], s[52:53], 0, v[184:185]
	v_lshl_add_u64 v[184:185], v[184:185], 0, s[78:79]
	v_lshl_add_u64 v[184:185], v[184:185], 0, s[4:5]
	v_lshlrev_b32_e32 v186, 1, v186
	v_mov_b32_e32 v187, 0
	v_lshl_add_u64 v[184:185], v[184:185], 0, v[186:187]
	v_add_co_u32_e32 v184, vcc, 0x3500000, v184
	s_nop 1
	v_addc_co_u32_e32 v185, vcc, 0, v185, vcc
	s_bitcmp1_b32 s12, 0
	s_cselect_b32 s22, 0x3900, 0
	s_and_saveexec_b64 s[6:7], s[42:43]
	s_cbranch_execz .LBB0_413

; #define LAS __attribute__((address_space(3)))
; __device__ __forceinline__ float sigmoidf_(float x) { return 1.0f / (1.0f + __expf(-x)); }
; __device__ __forceinline__ float softplusf_(float x) { return x > 20.f ? x : log1pf(expf(x)); }
; __device__ __forceinline__ float red8(float x) { x = red4(x); x += dppf<0x141>(x); return x; }
; __device__ __forceinline__ void u4f(const u32x4& u, float (&f)[8]) { h2f(u.x, f[0], f[1]); h2f(u.y, f[2], f[3]); h2f(u.z, f[4], f[5]); h2f(u.w, f[6], f[7]); }
; __device__ __forceinline__ void u2f(const u32x2& u, float (&f)[4]) { h2f(u.x, f[0], f[1]); h2f(u.y, f[2], f[3]); }
; template <int MIX, bool SAMPLE>
; __device__ __forceinline__ void rec_process(const Raw<MIX>& R, const MixPar& par, int l, LAS float* L, int chunk, int sg, int head) {
;     ...
;         float q[8], k[8], v[4]; u4f(R.q, q); u4f(R.k, k); u2f(R.v, v);
;         float sq = 0.f, sk = 0.f;
; #pragma unroll
;         for (int i = 0; i < 8; ++i) { sq += q[i] * q[i]; sk += k[i] * k[i]; }
;         sq = red8(sq); sk = red8(sk);
;         const float rq = rsqrtf(sq + EPS) * 0.125f, rk = rsqrtf(sk + EPS);
;         float kq = 0.f;
; #pragma unroll
;         for (int i = 0; i < 8; ++i) { q[i] *= rq; k[i] *= rk; kq += q[i] * k[i]; }
;         kq = red8(kq);
;         *(LAS f32x4*)(L + C::OFF_Q + s * 64 + cgi * 8) = (f32x4){q[0], q[1], q[2], q[3]}; *(LAS f32x4*)(L + C::OFF_Q + s * 64 + cgi * 8 + 4) = (f32x4){q[4], q[5], q[6], q[7]};
;         *(LAS f32x4*)(L + C::OFF_K + s * 64 + cgi * 8) = (f32x4){k[0], k[1], k[2], k[3]}; *(LAS f32x4*)(L + C::OFF_K + s * 64 + cgi * 8 + 4) = (f32x4){k[4], k[5], k[6], k[7]};
;         *(LAS f32x4*)(L + C::OFF_V + s * 32 + cgi * 4) = (f32x4){v[0], v[1], v[2], v[3]};
;         if (cgi == 0) { const float a = expf(-par.f[0] * softplusf_(R.ga + par.f[1]));
;             *(LAS f32x4*)(L + C::OFF_SC + s * 4) = (f32x4){a, sigmoidf_(R.gb), kq, 0.f}; }
.LBB0_413:
	s_or_b64 exec, exec, s[6:7]
	s_add_i32 s2, s12, 1
	s_cmp_lg_u32 s12, 31
	s_cbranch_scc0 .LBB0_420
	s_waitcnt vmcnt(0)
	v_cvt_f32_f16_e32 v23, v23
	v_cvt_f32_f16_e32 v24, v24
	v_cvt_f32_f16_sdwa v31, v0 dst_sel:DWORD dst_unused:UNUSED_PAD src0_sel:WORD_1
	v_cvt_f32_f16_e32 v30, v0
	s_waitcnt vmcnt(1)
	v_cvt_f32_f16_sdwa v47, v4 dst_sel:DWORD dst_unused:UNUSED_PAD src0_sel:WORD_1
	v_cvt_f32_f16_e32 v46, v4
	v_cvt_f32_f16_sdwa v41, v1 dst_sel:DWORD dst_unused:UNUSED_PAD src0_sel:WORD_1
	v_cvt_f32_f16_e32 v40, v1
	v_cvt_f32_f16_sdwa v49, v5 dst_sel:DWORD dst_unused:UNUSED_PAD src0_sel:WORD_1
	v_cvt_f32_f16_e32 v48, v5
	v_cvt_f32_f16_sdwa v15, v2 dst_sel:DWORD dst_unused:UNUSED_PAD src0_sel:WORD_1
	v_cvt_f32_f16_e32 v14, v2
	v_cvt_f32_f16_sdwa v43, v6 dst_sel:DWORD dst_unused:UNUSED_PAD src0_sel:WORD_1
	v_cvt_f32_f16_e32 v42, v6
	v_pk_mul_f32 v[38:39], v[30:31], v[30:31]
	v_pk_mul_f32 v[54:55], v[46:47], v[46:47]
	v_cvt_f32_f16_sdwa v37, v3 dst_sel:DWORD dst_unused:UNUSED_PAD src0_sel:WORD_1
	v_cvt_f32_f16_e32 v36, v3
	v_cvt_f32_f16_sdwa v45, v7 dst_sel:DWORD dst_unused:UNUSED_PAD src0_sel:WORD_1
	v_cvt_f32_f16_e32 v44, v7
	v_pk_fma_f32 v[38:39], v[40:41], v[40:41], v[38:39]
	v_pk_fma_f32 v[54:55], v[48:49], v[48:49], v[54:55]
	v_pk_fma_f32 v[38:39], v[14:15], v[14:15], v[38:39]
	v_pk_fma_f32 v[54:55], v[42:43], v[42:43], v[54:55]
	v_pk_fma_f32 v[38:39], v[36:37], v[36:37], v[38:39]
	v_pk_fma_f32 v[54:55], v[44:45], v[44:45], v[54:55]
	v_add_f32_e32 v29, v38, v39
	v_add_f32_e32 v28, v54, v55
	s_bitcmp1_b32 s2, 0
	s_cselect_b32 s3, 0xe400, 0
	v_mov_b32_dpp v33, v29 quad_perm:[1,0,3,2] row_mask:0xf bank_mask:0xf bound_ctrl:1
	v_mov_b32_dpp v32, v28 quad_perm:[1,0,3,2] row_mask:0xf bank_mask:0xf bound_ctrl:1
	v_pk_add_f32 v[28:29], v[28:29], v[32:33]
	s_add_i32 s3, s3, 0
	s_nop 0
	v_mov_b32_dpp v33, v29 quad_perm:[2,3,0,1] row_mask:0xf bank_mask:0xf bound_ctrl:1
	v_mov_b32_dpp v32, v28 quad_perm:[2,3,0,1] row_mask:0xf bank_mask:0xf bound_ctrl:1
	v_pk_add_f32 v[28:29], v[28:29], v[32:33]
	s_nop 1
	v_mov_b32_dpp v33, v29 row_half_mirror row_mask:0xf bank_mask:0xf bound_ctrl:1
	v_mov_b32_dpp v32, v28 row_half_mirror row_mask:0xf bank_mask:0xf bound_ctrl:1
	v_pk_add_f32 v[28:29], v[28:29], v[32:33]
	s_nop 0
	v_pk_add_f32 v[32:33], v[28:29], s[66:67] op_sel_hi:[1,0]
	v_mov_b32_e32 v29, v202
	s_nop 0
	v_rsq_f32_e32 v16, v33
	v_rsq_f32_e32 v38, v32
	v_ashrrev_i32_e32 v28, 3, v29
	v_mul_f32_e32 v16, 0x3e000000, v16
	v_pk_mul_f32 v[34:35], v[16:17], v[14:15] op_sel_hi:[0,1]
	v_pk_mul_f32 v[30:31], v[16:17], v[30:31] op_sel_hi:[0,1]
	v_pk_mul_f32 v[32:33], v[16:17], v[40:41] op_sel_hi:[0,1]
	v_pk_mul_f32 v[36:37], v[16:17], v[36:37] op_sel_hi:[0,1]
	v_mov_b32_e32 v14, v38
	v_pk_mul_f32 v[38:39], v[14:15], v[46:47] op_sel_hi:[0,1]
	v_pk_mul_f32 v[40:41], v[14:15], v[48:49] op_sel_hi:[0,1]
	v_cvt_f32_f16_sdwa v49, v9 dst_sel:DWORD dst_unused:UNUSED_PAD src0_sel:WORD_1
	v_pk_mul_f32 v[42:43], v[14:15], v[42:43] op_sel_hi:[0,1]
	v_cvt_f32_f16_e32 v48, v9
	v_pk_mul_f32 v[44:45], v[14:15], v[44:45] op_sel_hi:[0,1]
	v_cvt_f32_f16_sdwa v47, v8 dst_sel:DWORD dst_unused:UNUSED_PAD src0_sel:WORD_1
	v_and_b32_e32 v16, 7, v29
	v_cvt_f32_f16_e32 v46, v8
	v_lshlrev_b32_e32 v29, 8, v28
	v_lshlrev_b32_e32 v50, 5, v16
	v_add3_u32 v29, s3, v29, v50
	ds_write_b128 v29, v[30:33]
	ds_write_b128 v29, v[34:37] offset:16
	ds_write_b128 v29, v[38:41] offset:16384
	ds_write_b128 v29, v[42:45] offset:16400
	v_lshlrev_b32_e32 v29, 7, v28
	v_lshlrev_b32_e32 v30, 4, v16
	v_add3_u32 v29, s3, v29, v30
	v_cmp_eq_u32_e32 vcc, 0, v16
	v_mul_f32_e32 v60, 0xbfb8aa3b, v24
	v_exp_f32_e32 v60, v60
	s_nop 0
	v_add_f32_e32 v60, 1.0, v60
	v_rcp_f32_e32 v60, v60
	s_nop 0
	v_pk_mul_f32 v[46:47], v[46:47], v[60:61] op_sel_hi:[1,0]
	v_pk_mul_f32 v[48:49], v[48:49], v[60:61] op_sel_hi:[1,0]
	ds_write_b128 v29, v[46:49] offset:32768
	s_and_saveexec_b64 s[6:7], vcc
	s_cbranch_execz .LBB0_418
	v_add_f32_e32 v16, v18, v23
	v_cmp_nlt_f32_e32 vcc, s23, v16
	s_and_saveexec_b64 s[8:9], vcc
	s_cbranch_execz .LBB0_417
	v_mul_f32_e32 v29, 0x3fb8aa3b, v16
	v_rndne_f32_e32 v30, v29
	v_sub_f32_e32 v31, v29, v30
	v_fma_f32 v29, v16, s19, -v29
	v_fmac_f32_e32 v29, 0x32a5705f, v16
	v_add_f32_e32 v29, v31, v29
	v_cvt_i32_f32_e32 v30, v30
	v_exp_f32_e32 v29, v29
	v_cmp_ngt_f32_e32 vcc, s96, v16
	v_ldexp_f32 v29, v29, v30
	s_nop 0
	v_cndmask_b32_e32 v29, 0, v29, vcc
	v_cmp_nlt_f32_e32 vcc, s97, v16
	s_nop 1
	v_cndmask_b32_e32 v16, v216, v29, vcc
	v_add_f32_e32 v29, 1.0, v16
	v_add_f32_e32 v30, -1.0, v29
	v_log_f32_e32 v31, v29
	v_rcp_f32_e32 v29, v30
	v_cmp_eq_f32_e32 vcc, 0, v30
	v_mul_f32_e32 v31, 0x3f317218, v31
	v_mul_f32_e32 v29, v16, v29
	v_mul_f32_e32 v31, v31, v29
	v_cndmask_b32_e32 v16, v31, v16, vcc
